# prologue adaLN-modulation item: silu(c) staging loop loads batched 8 per pass; ada_w row loads issued 16 rows ahead (rolling prefetch) instead of two at a time
# speedup vs baseline: 1.0205x; 1.0020x over previous
.LBB0_32:
	s_movk_i32 s17, 0x2000
	v_ashrrev_i32_e32 v4, 31, v3
	v_lshrrev_b32_e32 v4, 21, v4
	v_add_u32_e32 v4, v3, v4
	v_ashrrev_i32_e32 v9, 11, v4
	v_and_b32_e32 v4, 0xfffff800, v4
	v_add_u32_e32 v11, 0xffffe000, v4
	v_cmp_gt_i32_e32 vcc, s17, v3
	v_mov_b32_e32 v5, s43
	v_mov_b32_e32 v6, s41
	v_mul_i32_i24_e32 v10, 0x800, v9
	v_cndmask_b32_e32 v11, v11, v4, vcc
	v_cndmask_b32_e32 v5, v5, v6, vcc
	v_sub_u32_e32 v6, v11, v10
	v_mov_b32_e32 v7, s42
	v_mov_b32_e32 v8, s40
	v_add_u32_e32 v6, v3, v6
	v_cndmask_b32_e32 v4, v7, v8, vcc
	v_ashrrev_i32_e32 v7, 31, v6
	v_lshl_add_u64 v[4:5], v[6:7], 2, v[4:5]
	global_load_dword v12, v[4:5], off
	v_lshlrev_b32_e32 v4, 2, v9
	v_mul_lo_u32 v6, v10, 48
	v_sub_u32_e32 v4, v4, v6
	v_add_u32_e32 v20, v2, v4
	v_add_u32_e32 v3, 0x200, v3
	v_add_u32_e32 v2, 0x6000, v2
	v_ashrrev_i32_e32 v4, 31, v3
	v_lshrrev_b32_e32 v4, 21, v4
	v_add_u32_e32 v4, v3, v4
	v_ashrrev_i32_e32 v9, 11, v4
	v_and_b32_e32 v4, 0xfffff800, v4
	v_add_u32_e32 v11, 0xffffe000, v4
	v_cmp_gt_i32_e32 vcc, s17, v3
	v_mov_b32_e32 v5, s43
	v_mov_b32_e32 v6, s41
	v_mul_i32_i24_e32 v10, 0x800, v9
	v_cndmask_b32_e32 v11, v11, v4, vcc
	v_cndmask_b32_e32 v5, v5, v6, vcc
	v_sub_u32_e32 v6, v11, v10
	v_mov_b32_e32 v7, s42
	v_mov_b32_e32 v8, s40
	v_add_u32_e32 v6, v3, v6
	v_cndmask_b32_e32 v4, v7, v8, vcc
	v_ashrrev_i32_e32 v7, 31, v6
	v_lshl_add_u64 v[4:5], v[6:7], 2, v[4:5]
	global_load_dword v13, v[4:5], off
	v_lshlrev_b32_e32 v4, 2, v9
	v_mul_lo_u32 v6, v10, 48
	v_sub_u32_e32 v4, v4, v6
	v_add_u32_e32 v21, v2, v4
	v_add_u32_e32 v3, 0x200, v3
	v_add_u32_e32 v2, 0x6000, v2
	v_ashrrev_i32_e32 v4, 31, v3
	v_lshrrev_b32_e32 v4, 21, v4
	v_add_u32_e32 v4, v3, v4
	v_ashrrev_i32_e32 v9, 11, v4
	v_and_b32_e32 v4, 0xfffff800, v4
	v_add_u32_e32 v11, 0xffffe000, v4
	v_cmp_gt_i32_e32 vcc, s17, v3
	v_mov_b32_e32 v5, s43
	v_mov_b32_e32 v6, s41
	v_mul_i32_i24_e32 v10, 0x800, v9
	v_cndmask_b32_e32 v11, v11, v4, vcc
	v_cndmask_b32_e32 v5, v5, v6, vcc
	v_sub_u32_e32 v6, v11, v10
	v_mov_b32_e32 v7, s42
	v_mov_b32_e32 v8, s40
	v_add_u32_e32 v6, v3, v6
	v_cndmask_b32_e32 v4, v7, v8, vcc
	v_ashrrev_i32_e32 v7, 31, v6
	v_lshl_add_u64 v[4:5], v[6:7], 2, v[4:5]
	global_load_dword v14, v[4:5], off
	v_lshlrev_b32_e32 v4, 2, v9
	v_mul_lo_u32 v6, v10, 48
	v_sub_u32_e32 v4, v4, v6
	v_add_u32_e32 v28, v2, v4
	v_add_u32_e32 v3, 0x200, v3
	v_add_u32_e32 v2, 0x6000, v2
	v_ashrrev_i32_e32 v4, 31, v3
	v_lshrrev_b32_e32 v4, 21, v4
	v_add_u32_e32 v4, v3, v4
	v_ashrrev_i32_e32 v9, 11, v4
	v_and_b32_e32 v4, 0xfffff800, v4
	v_add_u32_e32 v11, 0xffffe000, v4
	v_cmp_gt_i32_e32 vcc, s17, v3
	v_mov_b32_e32 v5, s43
	v_mov_b32_e32 v6, s41
	v_mul_i32_i24_e32 v10, 0x800, v9
	v_cndmask_b32_e32 v11, v11, v4, vcc
	v_cndmask_b32_e32 v5, v5, v6, vcc
	v_sub_u32_e32 v6, v11, v10
	v_mov_b32_e32 v7, s42
	v_mov_b32_e32 v8, s40
	v_add_u32_e32 v6, v3, v6
	v_cndmask_b32_e32 v4, v7, v8, vcc
	v_ashrrev_i32_e32 v7, 31, v6
	v_lshl_add_u64 v[4:5], v[6:7], 2, v[4:5]
	global_load_dword v15, v[4:5], off
	v_lshlrev_b32_e32 v4, 2, v9
	v_mul_lo_u32 v6, v10, 48
	v_sub_u32_e32 v4, v4, v6
	v_add_u32_e32 v29, v2, v4
	v_add_u32_e32 v3, 0x200, v3
	v_add_u32_e32 v2, 0x6000, v2
	v_ashrrev_i32_e32 v4, 31, v3
	v_lshrrev_b32_e32 v4, 21, v4
	v_add_u32_e32 v4, v3, v4
	v_ashrrev_i32_e32 v9, 11, v4
	v_and_b32_e32 v4, 0xfffff800, v4
	v_add_u32_e32 v11, 0xffffe000, v4
	v_cmp_gt_i32_e32 vcc, s17, v3
	v_mov_b32_e32 v5, s43
	v_mov_b32_e32 v6, s41
	v_mul_i32_i24_e32 v10, 0x800, v9
	v_cndmask_b32_e32 v11, v11, v4, vcc
	v_cndmask_b32_e32 v5, v5, v6, vcc
	v_sub_u32_e32 v6, v11, v10
	v_mov_b32_e32 v7, s42
	v_mov_b32_e32 v8, s40
	v_add_u32_e32 v6, v3, v6
	v_cndmask_b32_e32 v4, v7, v8, vcc
	v_ashrrev_i32_e32 v7, 31, v6
	v_lshl_add_u64 v[4:5], v[6:7], 2, v[4:5]
	global_load_dword v16, v[4:5], off
	v_lshlrev_b32_e32 v4, 2, v9
	v_mul_lo_u32 v6, v10, 48
	v_sub_u32_e32 v4, v4, v6
	v_add_u32_e32 v30, v2, v4
	v_add_u32_e32 v3, 0x200, v3
	v_add_u32_e32 v2, 0x6000, v2
	v_ashrrev_i32_e32 v4, 31, v3
	v_lshrrev_b32_e32 v4, 21, v4
	v_add_u32_e32 v4, v3, v4
	v_ashrrev_i32_e32 v9, 11, v4
	v_and_b32_e32 v4, 0xfffff800, v4
	v_add_u32_e32 v11, 0xffffe000, v4
	v_cmp_gt_i32_e32 vcc, s17, v3
	v_mov_b32_e32 v5, s43
	v_mov_b32_e32 v6, s41
	v_mul_i32_i24_e32 v10, 0x800, v9
	v_cndmask_b32_e32 v11, v11, v4, vcc
	v_cndmask_b32_e32 v5, v5, v6, vcc
	v_sub_u32_e32 v6, v11, v10
	v_mov_b32_e32 v7, s42
	v_mov_b32_e32 v8, s40
	v_add_u32_e32 v6, v3, v6
	v_cndmask_b32_e32 v4, v7, v8, vcc
	v_ashrrev_i32_e32 v7, 31, v6
	v_lshl_add_u64 v[4:5], v[6:7], 2, v[4:5]
	global_load_dword v17, v[4:5], off
	v_lshlrev_b32_e32 v4, 2, v9
	v_mul_lo_u32 v6, v10, 48
	v_sub_u32_e32 v4, v4, v6
	v_add_u32_e32 v31, v2, v4
	v_add_u32_e32 v3, 0x200, v3
	v_add_u32_e32 v2, 0x6000, v2
	v_ashrrev_i32_e32 v4, 31, v3
	v_lshrrev_b32_e32 v4, 21, v4
	v_add_u32_e32 v4, v3, v4
	v_ashrrev_i32_e32 v9, 11, v4
	v_and_b32_e32 v4, 0xfffff800, v4
	v_add_u32_e32 v11, 0xffffe000, v4
	v_cmp_gt_i32_e32 vcc, s17, v3
	v_mov_b32_e32 v5, s43
	v_mov_b32_e32 v6, s41
	v_mul_i32_i24_e32 v10, 0x800, v9
	v_cndmask_b32_e32 v11, v11, v4, vcc
	v_cndmask_b32_e32 v5, v5, v6, vcc
	v_sub_u32_e32 v6, v11, v10
	v_mov_b32_e32 v7, s42
	v_mov_b32_e32 v8, s40
	v_add_u32_e32 v6, v3, v6
	v_cndmask_b32_e32 v4, v7, v8, vcc
	v_ashrrev_i32_e32 v7, 31, v6
	v_lshl_add_u64 v[4:5], v[6:7], 2, v[4:5]
	global_load_dword v18, v[4:5], off
	v_lshlrev_b32_e32 v4, 2, v9
	v_mul_lo_u32 v6, v10, 48
	v_sub_u32_e32 v4, v4, v6
	v_add_u32_e32 v32, v2, v4
	v_add_u32_e32 v3, 0x200, v3
	v_add_u32_e32 v2, 0x6000, v2
	v_ashrrev_i32_e32 v4, 31, v3
	v_lshrrev_b32_e32 v4, 21, v4
	v_add_u32_e32 v4, v3, v4
	v_ashrrev_i32_e32 v9, 11, v4
	v_and_b32_e32 v4, 0xfffff800, v4
	v_add_u32_e32 v11, 0xffffe000, v4
	v_cmp_gt_i32_e32 vcc, s17, v3
	v_mov_b32_e32 v5, s43
	v_mov_b32_e32 v6, s41
	v_mul_i32_i24_e32 v10, 0x800, v9
	v_cndmask_b32_e32 v11, v11, v4, vcc
	v_cndmask_b32_e32 v5, v5, v6, vcc
	v_sub_u32_e32 v6, v11, v10
	v_mov_b32_e32 v7, s42
	v_mov_b32_e32 v8, s40
	v_add_u32_e32 v6, v3, v6
	v_cndmask_b32_e32 v4, v7, v8, vcc
	v_ashrrev_i32_e32 v7, 31, v6
	v_lshl_add_u64 v[4:5], v[6:7], 2, v[4:5]
	global_load_dword v19, v[4:5], off
	v_lshlrev_b32_e32 v4, 2, v9
	v_mul_lo_u32 v6, v10, 48
	v_sub_u32_e32 v4, v4, v6
	v_add_u32_e32 v33, v2, v4
	v_add_u32_e32 v3, 0x200, v3
	v_add_u32_e32 v2, 0x6000, v2
	s_waitcnt vmcnt(0)
	v_mul_f32_e32 v4, 0xbfb8aa3b, v12
	v_exp_f32_e32 v7, v4
	s_nop 0
	v_add_f32_e32 v5, 1.0, v7
	v_div_scale_f32 v7, s[18:19], v5, v5, v12
	v_rcp_f32_e32 v8, v7
	v_div_scale_f32 v9, vcc, v12, v5, v12
	v_fma_f32 v10, -v7, v8, 1.0
	v_fmac_f32_e32 v8, v10, v8
	v_mul_f32_e32 v10, v9, v8
	v_fma_f32 v11, -v7, v10, v9
	v_fmac_f32_e32 v10, v11, v8
	v_fma_f32 v7, -v7, v10, v9
	v_div_fmas_f32 v7, v7, v8, v10
	v_div_fixup_f32 v4, v7, v5, v12
	ds_write_b32 v20, v4
	v_mul_f32_e32 v4, 0xbfb8aa3b, v13
	v_exp_f32_e32 v7, v4
	s_nop 0
	v_add_f32_e32 v5, 1.0, v7
	v_div_scale_f32 v7, s[18:19], v5, v5, v13
	v_rcp_f32_e32 v8, v7
	v_div_scale_f32 v9, vcc, v13, v5, v13
	v_fma_f32 v10, -v7, v8, 1.0
	v_fmac_f32_e32 v8, v10, v8
	v_mul_f32_e32 v10, v9, v8
	v_fma_f32 v11, -v7, v10, v9
	v_fmac_f32_e32 v10, v11, v8
	v_fma_f32 v7, -v7, v10, v9
	v_div_fmas_f32 v7, v7, v8, v10
	v_div_fixup_f32 v4, v7, v5, v13
	ds_write_b32 v21, v4
	v_mul_f32_e32 v4, 0xbfb8aa3b, v14
	v_exp_f32_e32 v7, v4
	s_nop 0
	v_add_f32_e32 v5, 1.0, v7
	v_div_scale_f32 v7, s[18:19], v5, v5, v14
	v_rcp_f32_e32 v8, v7
	v_div_scale_f32 v9, vcc, v14, v5, v14
	v_fma_f32 v10, -v7, v8, 1.0
	v_fmac_f32_e32 v8, v10, v8
	v_mul_f32_e32 v10, v9, v8
	v_fma_f32 v11, -v7, v10, v9
	v_fmac_f32_e32 v10, v11, v8
	v_fma_f32 v7, -v7, v10, v9
	v_div_fmas_f32 v7, v7, v8, v10
	v_div_fixup_f32 v4, v7, v5, v14
	ds_write_b32 v28, v4
	v_mul_f32_e32 v4, 0xbfb8aa3b, v15
	v_exp_f32_e32 v7, v4
	s_nop 0
	v_add_f32_e32 v5, 1.0, v7
	v_div_scale_f32 v7, s[18:19], v5, v5, v15
	v_rcp_f32_e32 v8, v7
	v_div_scale_f32 v9, vcc, v15, v5, v15
	v_fma_f32 v10, -v7, v8, 1.0
	v_fmac_f32_e32 v8, v10, v8
	v_mul_f32_e32 v10, v9, v8
	v_fma_f32 v11, -v7, v10, v9
	v_fmac_f32_e32 v10, v11, v8
	v_fma_f32 v7, -v7, v10, v9
	v_div_fmas_f32 v7, v7, v8, v10
	v_div_fixup_f32 v4, v7, v5, v15
	ds_write_b32 v29, v4
	v_mul_f32_e32 v4, 0xbfb8aa3b, v16
	v_exp_f32_e32 v7, v4
	s_nop 0
	v_add_f32_e32 v5, 1.0, v7
	v_div_scale_f32 v7, s[18:19], v5, v5, v16
	v_rcp_f32_e32 v8, v7
	v_div_scale_f32 v9, vcc, v16, v5, v16
	v_fma_f32 v10, -v7, v8, 1.0
	v_fmac_f32_e32 v8, v10, v8
	v_mul_f32_e32 v10, v9, v8
	v_fma_f32 v11, -v7, v10, v9
	v_fmac_f32_e32 v10, v11, v8
	v_fma_f32 v7, -v7, v10, v9
	v_div_fmas_f32 v7, v7, v8, v10
	v_div_fixup_f32 v4, v7, v5, v16
	ds_write_b32 v30, v4
	v_mul_f32_e32 v4, 0xbfb8aa3b, v17
	v_exp_f32_e32 v7, v4
	s_nop 0
	v_add_f32_e32 v5, 1.0, v7
	v_div_scale_f32 v7, s[18:19], v5, v5, v17
	v_rcp_f32_e32 v8, v7
	v_div_scale_f32 v9, vcc, v17, v5, v17
	v_fma_f32 v10, -v7, v8, 1.0
	v_fmac_f32_e32 v8, v10, v8
	v_mul_f32_e32 v10, v9, v8
	v_fma_f32 v11, -v7, v10, v9
	v_fmac_f32_e32 v10, v11, v8
	v_fma_f32 v7, -v7, v10, v9
	v_div_fmas_f32 v7, v7, v8, v10
	v_div_fixup_f32 v4, v7, v5, v17
	ds_write_b32 v31, v4
	v_mul_f32_e32 v4, 0xbfb8aa3b, v18
	v_exp_f32_e32 v7, v4
	s_nop 0
	v_add_f32_e32 v5, 1.0, v7
	v_div_scale_f32 v7, s[18:19], v5, v5, v18
	v_rcp_f32_e32 v8, v7
	v_div_scale_f32 v9, vcc, v18, v5, v18
	v_fma_f32 v10, -v7, v8, 1.0
	v_fmac_f32_e32 v8, v10, v8
	v_mul_f32_e32 v10, v9, v8
	v_fma_f32 v11, -v7, v10, v9
	v_fmac_f32_e32 v10, v11, v8
	v_fma_f32 v7, -v7, v10, v9
	v_div_fmas_f32 v7, v7, v8, v10
	v_div_fixup_f32 v4, v7, v5, v18
	ds_write_b32 v32, v4
	v_mul_f32_e32 v4, 0xbfb8aa3b, v19
	v_exp_f32_e32 v7, v4
	s_nop 0
	v_add_f32_e32 v5, 1.0, v7
	v_div_scale_f32 v7, s[18:19], v5, v5, v19
	v_rcp_f32_e32 v8, v7
	v_div_scale_f32 v9, vcc, v19, v5, v19
	v_fma_f32 v10, -v7, v8, 1.0
	v_fmac_f32_e32 v8, v10, v8
	v_mul_f32_e32 v10, v9, v8
	v_fma_f32 v11, -v7, v10, v9
	v_fmac_f32_e32 v10, v11, v8
	v_fma_f32 v7, -v7, v10, v9
	v_div_fmas_f32 v7, v7, v8, v10
	v_div_fixup_f32 v4, v7, v5, v19
	ds_write_b32 v33, v4
	s_movk_i32 s17, 0x5fff
	v_cmp_lt_i32_e32 vcc, s17, v3
	s_or_b64 s[14:15], vcc, s[14:15]
	s_andn2_b64 exec, exec, s[14:15]
	s_cbranch_execnz .LBB0_32
.LBB0_33:
	s_or_b64 exec, exec, s[12:13]
	s_lshl_b32 s12, s16, 8
	s_ashr_i32 s13, s12, 31
	v_mov_b32_e32 v6, 0
	v_lshl_add_u64 v[56:57], s[12:13], 2, v[54:55]
	s_mov_b32 s16, s25
	s_mov_b32 s17, s24
	v_mov_b32_e32 v7, v6
	v_mov_b32_e32 v8, v6
	v_mov_b32_e32 v9, v6
	v_mov_b32_e32 v10, v6
	v_mov_b32_e32 v11, v6
	v_mov_b32_e32 v12, v6
	v_mov_b32_e32 v13, v6
	v_mov_b32_e32 v14, v6
	v_mov_b32_e32 v15, v6
	v_mov_b32_e32 v16, v6
	v_mov_b32_e32 v17, v6
	v_mov_b32_e32 v28, v6
	v_mov_b32_e32 v29, v6
	v_mov_b32_e32 v30, v6
	v_mov_b32_e32 v31, v6
	v_mov_b32_e32 v32, v6
	v_mov_b32_e32 v33, v6
	v_mov_b32_e32 v34, v6
	v_mov_b32_e32 v35, v6
	v_mov_b32_e32 v36, v6
	v_mov_b32_e32 v37, v6
	v_mov_b32_e32 v38, v6
	v_mov_b32_e32 v39, v6
	v_mov_b32_e32 v18, v6
	v_mov_b32_e32 v19, v6
	v_mov_b32_e32 v20, v6
	v_mov_b32_e32 v21, v6
	v_mov_b32_e32 v40, v6
	v_mov_b32_e32 v41, v6
	v_mov_b32_e32 v42, v6
	v_mov_b32_e32 v43, v6
	v_mov_b32_e32 v44, v6
	v_mov_b32_e32 v45, v6
	v_mov_b32_e32 v46, v6
	v_mov_b32_e32 v47, v6
	v_mov_b32_e32 v48, v6
	v_mov_b32_e32 v49, v6
	v_mov_b32_e32 v50, v6
	v_mov_b32_e32 v51, v6
	v_mov_b32_e32 v22, v6
	v_mov_b32_e32 v23, v6
	v_mov_b32_e32 v24, v6
	v_mov_b32_e32 v25, v6
	v_mov_b32_e32 v2, v6
	v_mov_b32_e32 v3, v6
	v_mov_b32_e32 v4, v6
	v_mov_b32_e32 v5, v6
	s_waitcnt lgkmcnt(0)
	s_barrier
	v_add_co_u32_e32 v194, vcc, 0xfff4c000, v56
	s_nop 1
	v_addc_co_u32_e32 v195, vcc, -1, v57, vcc
	global_load_dwordx4 v[130:133], v[194:195], off nt
	v_add_co_u32_e32 v194, vcc, 0xfff58000, v56
	s_nop 1
	v_addc_co_u32_e32 v195, vcc, -1, v57, vcc
	global_load_dwordx4 v[134:137], v[194:195], off nt
	v_add_co_u32_e32 v194, vcc, 0xfff64000, v56
	s_nop 1
	v_addc_co_u32_e32 v195, vcc, -1, v57, vcc
	global_load_dwordx4 v[138:141], v[194:195], off nt
	v_add_co_u32_e32 v194, vcc, 0xfff70000, v56
	s_nop 1
	v_addc_co_u32_e32 v195, vcc, -1, v57, vcc
	global_load_dwordx4 v[142:145], v[194:195], off nt
	v_add_co_u32_e32 v194, vcc, 0xfff7c000, v56
	s_nop 1
	v_addc_co_u32_e32 v195, vcc, -1, v57, vcc
	global_load_dwordx4 v[146:149], v[194:195], off nt
	v_add_co_u32_e32 v194, vcc, 0xfff88000, v56
	s_nop 1
	v_addc_co_u32_e32 v195, vcc, -1, v57, vcc
	global_load_dwordx4 v[150:153], v[194:195], off nt
	v_add_co_u32_e32 v194, vcc, 0xfff94000, v56
	s_nop 1
	v_addc_co_u32_e32 v195, vcc, -1, v57, vcc
	global_load_dwordx4 v[154:157], v[194:195], off nt
	v_add_co_u32_e32 v194, vcc, 0xfffa0000, v56
	s_nop 1
	v_addc_co_u32_e32 v195, vcc, -1, v57, vcc
	global_load_dwordx4 v[158:161], v[194:195], off nt
	v_add_co_u32_e32 v194, vcc, 0xfffac000, v56
	s_nop 1
	v_addc_co_u32_e32 v195, vcc, -1, v57, vcc
	global_load_dwordx4 v[162:165], v[194:195], off nt
	v_add_co_u32_e32 v194, vcc, 0xfffb8000, v56
	s_nop 1
	v_addc_co_u32_e32 v195, vcc, -1, v57, vcc
	global_load_dwordx4 v[166:169], v[194:195], off nt
	v_add_co_u32_e32 v194, vcc, 0xfffc4000, v56
	s_nop 1
	v_addc_co_u32_e32 v195, vcc, -1, v57, vcc
	global_load_dwordx4 v[170:173], v[194:195], off nt
	v_add_co_u32_e32 v194, vcc, 0xfffd0000, v56
	s_nop 1
	v_addc_co_u32_e32 v195, vcc, -1, v57, vcc
	global_load_dwordx4 v[174:177], v[194:195], off nt
	v_add_co_u32_e32 v194, vcc, 0xfffdc000, v56
	s_nop 1
	v_addc_co_u32_e32 v195, vcc, -1, v57, vcc
	global_load_dwordx4 v[178:181], v[194:195], off nt
	v_add_co_u32_e32 v194, vcc, 0xfffe8000, v56
	s_nop 1
	v_addc_co_u32_e32 v195, vcc, -1, v57, vcc
	global_load_dwordx4 v[182:185], v[194:195], off nt
	v_add_co_u32_e32 v194, vcc, 0xffff4000, v56
	s_nop 1
	v_addc_co_u32_e32 v195, vcc, -1, v57, vcc
	global_load_dwordx4 v[186:189], v[194:195], off nt
	global_load_dwordx4 v[190:193], v[56:57], off nt
.LBB0_34:
	s_mov_b32 s14, 0xfff4c000
	v_add_co_u32_e32 v26, vcc, s14, v56
	s_mov_b32 s14, 0xfff58000
	s_nop 0
	v_addc_co_u32_e32 v27, vcc, -1, v57, vcc
	v_add_co_u32_e32 v62, vcc, s14, v56
	v_mov_b32_e32 v77, s16
	s_nop 0
	v_addc_co_u32_e32 v63, vcc, -1, v57, vcc
	s_waitcnt vmcnt(15)
	v_mov_b64_e32 v[58:59], v[130:131]
	v_mov_b64_e32 v[60:61], v[132:133]
	v_add_co_u32_e32 v194, vcc, 0xc000, v56
	s_nop 1
	v_addc_co_u32_e32 v195, vcc, 0, v57, vcc
	global_load_dwordx4 v[130:133], v[194:195], off nt
	s_nop 0
	s_waitcnt vmcnt(15)
	v_mov_b64_e32 v[62:63], v[134:135]
	v_mov_b64_e32 v[64:65], v[136:137]
	v_add_co_u32_e32 v194, vcc, 0x18000, v56
	s_nop 1
	v_addc_co_u32_e32 v195, vcc, 0, v57, vcc
	global_load_dwordx4 v[134:137], v[194:195], off nt
	ds_read_b128 v[66:69], v77
	ds_read_b128 v[70:73], v77 offset:16
	s_mov_b32 s14, 0xfff64000
	s_add_i32 s17, s17, 16
	s_addk_i32 s16, 0x300
	s_cmp_ge_i32 s17, s23
	s_waitcnt lgkmcnt(1)
	v_pk_fma_f32 v[74:75], v[58:59], v[66:67], v[6:7] op_sel_hi:[1,0,1]
	v_mov_b32_e32 v6, v69
	v_pk_fma_f32 v[26:27], v[60:61], v[66:67], v[8:9] op_sel_hi:[1,0,1]
	v_pk_fma_f32 v[16:17], v[60:61], v[68:69], v[16:17] op_sel_hi:[1,0,1]
	v_pk_fma_f32 v[14:15], v[58:59], v[68:69], v[14:15] op_sel_hi:[1,0,1]
	v_pk_fma_f32 v[30:31], v[60:61], v[6:7], v[30:31] op_sel_hi:[1,0,1]
	v_pk_fma_f32 v[68:69], v[58:59], v[6:7], v[28:29] op_sel_hi:[1,0,1]
	ds_read_b128 v[6:9], v77 offset:32
	v_pk_fma_f32 v[78:79], v[60:61], v[66:67], v[12:13] op_sel:[0,1,0]
	v_pk_fma_f32 v[66:67], v[58:59], v[66:67], v[10:11] op_sel:[0,1,0]
	s_waitcnt lgkmcnt(1)
	v_mov_b32_e32 v10, v73
	v_pk_fma_f32 v[28:29], v[60:61], v[70:71], v[34:35] op_sel_hi:[1,0,1]
	v_pk_fma_f32 v[34:35], v[60:61], v[70:71], v[38:39] op_sel:[0,1,0]
	v_pk_fma_f32 v[38:39], v[60:61], v[10:11], v[42:43] op_sel_hi:[1,0,1]
	v_pk_fma_f32 v[40:41], v[58:59], v[10:11], v[40:41] op_sel_hi:[1,0,1]
	ds_read_b128 v[10:13], v77 offset:48
	s_waitcnt lgkmcnt(1)
	v_pk_fma_f32 v[42:43], v[60:61], v[6:7], v[46:47] op_sel_hi:[1,0,1]
	v_pk_fma_f32 v[44:45], v[58:59], v[6:7], v[44:45] op_sel_hi:[1,0,1]
	v_pk_fma_f32 v[46:47], v[60:61], v[6:7], v[50:51] op_sel:[0,1,0]
	v_pk_fma_f32 v[48:49], v[58:59], v[6:7], v[48:49] op_sel:[0,1,0]
	v_mov_b32_e32 v6, v9
	v_pk_fma_f32 v[32:33], v[58:59], v[70:71], v[32:33] op_sel_hi:[1,0,1]
	v_pk_fma_f32 v[36:37], v[58:59], v[70:71], v[36:37] op_sel:[0,1,0]
	v_pk_fma_f32 v[18:19], v[58:59], v[72:73], v[18:19] op_sel_hi:[1,0,1]
	v_pk_fma_f32 v[22:23], v[58:59], v[8:9], v[22:23] op_sel_hi:[1,0,1]
	v_pk_fma_f32 v[50:51], v[60:61], v[6:7], v[4:5] op_sel_hi:[1,0,1]
	v_pk_fma_f32 v[58:59], v[58:59], v[6:7], v[2:3] op_sel_hi:[1,0,1]
	ds_read_b128 v[2:5], v77 offset:64
	v_pk_fma_f32 v[20:21], v[60:61], v[72:73], v[20:21] op_sel_hi:[1,0,1]
	v_pk_fma_f32 v[24:25], v[60:61], v[8:9], v[24:25] op_sel_hi:[1,0,1]
	v_add_co_u32_e32 v60, vcc, s14, v56
	s_waitcnt lgkmcnt(1)
	v_pk_fma_f32 v[72:73], v[64:65], v[10:11], v[26:27] op_sel_hi:[1,0,1]
	v_addc_co_u32_e32 v61, vcc, -1, v57, vcc
	ds_read_b128 v[6:9], v77 offset:80
	s_waitcnt lgkmcnt(1)
	v_pk_fma_f32 v[80:81], v[64:65], v[2:3], v[28:29] op_sel_hi:[1,0,1]
	s_waitcnt vmcnt(15)
	v_mov_b64_e32 v[26:27], v[138:139]
	v_mov_b64_e32 v[28:29], v[140:141]
	v_add_co_u32_e32 v194, vcc, 0x24000, v56
	s_nop 1
	v_addc_co_u32_e32 v195, vcc, 0, v57, vcc
	global_load_dwordx4 v[138:141], v[194:195], off nt
	s_mov_b32 s14, 0xfff70000
	v_pk_fma_f32 v[20:21], v[64:65], v[4:5], v[20:21] op_sel_hi:[1,0,1]
	v_pk_fma_f32 v[18:19], v[62:63], v[4:5], v[18:19] op_sel_hi:[1,0,1]
	v_add_co_u32_e32 v4, vcc, s14, v56
	v_pk_fma_f32 v[32:33], v[62:63], v[2:3], v[32:33] op_sel_hi:[1,0,1]
	v_pk_fma_f32 v[34:35], v[64:65], v[2:3], v[34:35] op_sel:[0,1,0]
	v_pk_fma_f32 v[36:37], v[62:63], v[2:3], v[36:37] op_sel:[0,1,0]
	v_mov_b32_e32 v2, v5
	v_addc_co_u32_e32 v5, vcc, -1, v57, vcc
	v_pk_fma_f32 v[74:75], v[62:63], v[10:11], v[74:75] op_sel_hi:[1,0,1]
	v_pk_fma_f32 v[78:79], v[64:65], v[10:11], v[78:79] op_sel:[0,1,0]
	v_pk_fma_f32 v[66:67], v[62:63], v[10:11], v[66:67] op_sel:[0,1,0]
	s_waitcnt lgkmcnt(0)
	v_pk_fma_f32 v[42:43], v[64:65], v[6:7], v[42:43] op_sel_hi:[1,0,1]
	v_pk_fma_f32 v[44:45], v[62:63], v[6:7], v[44:45] op_sel_hi:[1,0,1]
	v_pk_fma_f32 v[46:47], v[64:65], v[6:7], v[46:47] op_sel:[0,1,0]
	v_pk_fma_f32 v[48:49], v[62:63], v[6:7], v[48:49] op_sel:[0,1,0]
	v_pk_fma_f32 v[24:25], v[64:65], v[8:9], v[24:25] op_sel_hi:[1,0,1]
	v_pk_fma_f32 v[82:83], v[62:63], v[8:9], v[22:23] op_sel_hi:[1,0,1]
	v_mov_b32_e32 v10, v9
	s_waitcnt vmcnt(15)
	v_mov_b64_e32 v[6:7], v[142:143]
	v_mov_b64_e32 v[8:9], v[144:145]
	v_add_co_u32_e32 v194, vcc, 0x30000, v56
	s_nop 1
	v_addc_co_u32_e32 v195, vcc, 0, v57, vcc
	global_load_dwordx4 v[142:145], v[194:195], off nt
	v_mov_b32_e32 v70, v13
	v_pk_fma_f32 v[16:17], v[64:65], v[12:13], v[16:17] op_sel_hi:[1,0,1]
	v_pk_fma_f32 v[14:15], v[62:63], v[12:13], v[14:15] op_sel_hi:[1,0,1]
	v_pk_fma_f32 v[38:39], v[64:65], v[2:3], v[38:39] op_sel_hi:[1,0,1]
	v_pk_fma_f32 v[40:41], v[62:63], v[2:3], v[40:41] op_sel_hi:[1,0,1]
	v_pk_fma_f32 v[50:51], v[64:65], v[10:11], v[50:51] op_sel_hi:[1,0,1]
	v_pk_fma_f32 v[58:59], v[62:63], v[10:11], v[58:59] op_sel_hi:[1,0,1]
	ds_read_b128 v[2:5], v77 offset:96
	ds_read_b128 v[10:13], v77 offset:112
	v_pk_fma_f32 v[60:61], v[64:65], v[70:71], v[30:31] op_sel_hi:[1,0,1]
	v_pk_fma_f32 v[68:69], v[62:63], v[70:71], v[68:69] op_sel_hi:[1,0,1]
	s_mov_b32 s14, 0xfff7c000
	s_waitcnt lgkmcnt(0)
	v_mov_b32_e32 v84, v13
	v_pk_fma_f32 v[62:63], v[28:29], v[2:3], v[72:73] op_sel_hi:[1,0,1]
	v_pk_fma_f32 v[64:65], v[26:27], v[2:3], v[74:75] op_sel_hi:[1,0,1]
	v_pk_fma_f32 v[70:71], v[28:29], v[2:3], v[78:79] op_sel:[0,1,0]
	v_pk_fma_f32 v[66:67], v[26:27], v[2:3], v[66:67] op_sel:[0,1,0]
	v_pk_fma_f32 v[72:73], v[28:29], v[4:5], v[16:17] op_sel_hi:[1,0,1]
	v_pk_fma_f32 v[74:75], v[26:27], v[4:5], v[14:15] op_sel_hi:[1,0,1]
	v_mov_b32_e32 v78, v5
	v_pk_fma_f32 v[86:87], v[26:27], v[10:11], v[32:33] op_sel_hi:[1,0,1]
	ds_read_b128 v[2:5], v77 offset:128
	ds_read_b128 v[30:33], v77 offset:144
	v_pk_fma_f32 v[80:81], v[28:29], v[10:11], v[80:81] op_sel_hi:[1,0,1]
	v_pk_fma_f32 v[34:35], v[28:29], v[10:11], v[34:35] op_sel:[0,1,0]
	v_pk_fma_f32 v[36:37], v[26:27], v[10:11], v[36:37] op_sel:[0,1,0]
	s_waitcnt lgkmcnt(1)
	v_pk_fma_f32 v[14:15], v[28:29], v[2:3], v[42:43] op_sel_hi:[1,0,1]
	v_mov_b32_e32 v42, v5
	v_pk_fma_f32 v[88:89], v[28:29], v[12:13], v[20:21] op_sel_hi:[1,0,1]
	v_pk_fma_f32 v[90:91], v[26:27], v[12:13], v[18:19] op_sel_hi:[1,0,1]
	v_pk_fma_f32 v[16:17], v[26:27], v[2:3], v[44:45] op_sel_hi:[1,0,1]
	v_pk_fma_f32 v[18:19], v[28:29], v[2:3], v[46:47] op_sel:[0,1,0]
	v_pk_fma_f32 v[20:21], v[26:27], v[2:3], v[48:49] op_sel:[0,1,0]
	v_pk_fma_f32 v[22:23], v[28:29], v[4:5], v[24:25] op_sel_hi:[1,0,1]
	v_pk_fma_f32 v[24:25], v[26:27], v[4:5], v[82:83] op_sel_hi:[1,0,1]
	v_pk_fma_f32 v[2:3], v[28:29], v[78:79], v[60:61] op_sel_hi:[1,0,1]
	v_pk_fma_f32 v[4:5], v[26:27], v[78:79], v[68:69] op_sel_hi:[1,0,1]
	v_pk_fma_f32 v[10:11], v[28:29], v[84:85], v[38:39] op_sel_hi:[1,0,1]
	v_pk_fma_f32 v[12:13], v[26:27], v[84:85], v[40:41] op_sel_hi:[1,0,1]
	v_pk_fma_f32 v[40:41], v[28:29], v[42:43], v[50:51] op_sel_hi:[1,0,1]
	v_pk_fma_f32 v[42:43], v[26:27], v[42:43], v[58:59] op_sel_hi:[1,0,1]
	ds_read_b128 v[26:29], v77 offset:160
	v_add_co_u32_e32 v38, vcc, s14, v56
	s_waitcnt lgkmcnt(1)
	v_mov_b32_e32 v44, v33
	v_addc_co_u32_e32 v39, vcc, -1, v57, vcc
	v_pk_fma_f32 v[46:47], v[8:9], v[30:31], v[62:63] op_sel_hi:[1,0,1]
	v_pk_fma_f32 v[48:49], v[6:7], v[30:31], v[64:65] op_sel_hi:[1,0,1]
	v_pk_fma_f32 v[50:51], v[8:9], v[30:31], v[70:71] op_sel:[0,1,0]
	v_pk_fma_f32 v[58:59], v[6:7], v[30:31], v[66:67] op_sel:[0,1,0]
	v_pk_fma_f32 v[60:61], v[8:9], v[32:33], v[72:73] op_sel_hi:[1,0,1]
	v_pk_fma_f32 v[62:63], v[6:7], v[32:33], v[74:75] op_sel_hi:[1,0,1]
	ds_read_b128 v[30:33], v77 offset:176
	s_waitcnt lgkmcnt(1)
	v_pk_fma_f32 v[64:65], v[8:9], v[26:27], v[80:81] op_sel_hi:[1,0,1]
	v_pk_fma_f32 v[66:67], v[6:7], v[26:27], v[86:87] op_sel_hi:[1,0,1]
	v_pk_fma_f32 v[34:35], v[8:9], v[26:27], v[34:35] op_sel:[0,1,0]
	v_pk_fma_f32 v[36:37], v[6:7], v[26:27], v[36:37] op_sel:[0,1,0]
	v_pk_fma_f32 v[68:69], v[8:9], v[28:29], v[88:89] op_sel_hi:[1,0,1]
	v_pk_fma_f32 v[70:71], v[6:7], v[28:29], v[90:91] op_sel_hi:[1,0,1]
	v_mov_b32_e32 v72, v29
	s_waitcnt vmcnt(15)
	v_mov_b64_e32 v[26:27], v[146:147]
	v_mov_b64_e32 v[28:29], v[148:149]
	v_add_co_u32_e32 v194, vcc, 0x3c000, v56
	s_nop 1
	v_addc_co_u32_e32 v195, vcc, 0, v57, vcc
	global_load_dwordx4 v[146:149], v[194:195], off nt
	s_mov_b32 s14, 0xfff88000
	v_add_co_u32_e32 v74, vcc, s14, v56
	v_pk_fma_f32 v[38:39], v[8:9], v[44:45], v[2:3] op_sel_hi:[1,0,1]
	s_nop 0
	v_addc_co_u32_e32 v75, vcc, -1, v57, vcc
	v_pk_fma_f32 v[44:45], v[6:7], v[44:45], v[4:5] op_sel_hi:[1,0,1]
	s_waitcnt vmcnt(15)
	v_mov_b64_e32 v[2:3], v[150:151]
	v_mov_b64_e32 v[4:5], v[152:153]
	v_add_co_u32_e32 v194, vcc, 0x48000, v56
	s_nop 1
	v_addc_co_u32_e32 v195, vcc, 0, v57, vcc
	global_load_dwordx4 v[150:153], v[194:195], off nt
	s_waitcnt lgkmcnt(0)
	v_pk_fma_f32 v[14:15], v[8:9], v[30:31], v[14:15] op_sel_hi:[1,0,1]
	v_pk_fma_f32 v[16:17], v[6:7], v[30:31], v[16:17] op_sel_hi:[1,0,1]
	v_pk_fma_f32 v[18:19], v[8:9], v[30:31], v[18:19] op_sel:[0,1,0]
	v_pk_fma_f32 v[20:21], v[6:7], v[30:31], v[20:21] op_sel:[0,1,0]
	v_mov_b32_e32 v30, v33
	v_pk_fma_f32 v[22:23], v[8:9], v[32:33], v[22:23] op_sel_hi:[1,0,1]
	v_pk_fma_f32 v[24:25], v[6:7], v[32:33], v[24:25] op_sel_hi:[1,0,1]
	v_pk_fma_f32 v[74:75], v[8:9], v[72:73], v[10:11] op_sel_hi:[1,0,1]
	v_pk_fma_f32 v[72:73], v[6:7], v[72:73], v[12:13] op_sel_hi:[1,0,1]
	v_pk_fma_f32 v[40:41], v[8:9], v[30:31], v[40:41] op_sel_hi:[1,0,1]
	v_pk_fma_f32 v[42:43], v[6:7], v[30:31], v[42:43] op_sel_hi:[1,0,1]
	ds_read_b128 v[6:9], v77 offset:192
	ds_read_b128 v[10:13], v77 offset:208
	s_mov_b32 s14, 0xfff94000
	s_waitcnt lgkmcnt(1)
	v_mov_b32_e32 v78, v9
	s_waitcnt lgkmcnt(0)
	v_mov_b32_e32 v80, v13
	v_pk_fma_f32 v[46:47], v[28:29], v[6:7], v[46:47] op_sel_hi:[1,0,1]
	v_pk_fma_f32 v[48:49], v[26:27], v[6:7], v[48:49] op_sel_hi:[1,0,1]
	v_pk_fma_f32 v[50:51], v[28:29], v[6:7], v[50:51] op_sel:[0,1,0]
	v_pk_fma_f32 v[58:59], v[26:27], v[6:7], v[58:59] op_sel:[0,1,0]
	v_pk_fma_f32 v[60:61], v[28:29], v[8:9], v[60:61] op_sel_hi:[1,0,1]
	v_pk_fma_f32 v[62:63], v[26:27], v[8:9], v[62:63] op_sel_hi:[1,0,1]
	ds_read_b128 v[6:9], v77 offset:224
	ds_read_b128 v[30:33], v77 offset:240
	v_pk_fma_f32 v[64:65], v[28:29], v[10:11], v[64:65] op_sel_hi:[1,0,1]
	v_pk_fma_f32 v[66:67], v[26:27], v[10:11], v[66:67] op_sel_hi:[1,0,1]
	v_pk_fma_f32 v[34:35], v[28:29], v[10:11], v[34:35] op_sel:[0,1,0]
	s_waitcnt lgkmcnt(1)
	v_mov_b32_e32 v82, v9
	v_pk_fma_f32 v[36:37], v[26:27], v[10:11], v[36:37] op_sel:[0,1,0]
	v_pk_fma_f32 v[68:69], v[28:29], v[12:13], v[68:69] op_sel_hi:[1,0,1]
	v_pk_fma_f32 v[70:71], v[26:27], v[12:13], v[70:71] op_sel_hi:[1,0,1]
	v_pk_fma_f32 v[14:15], v[28:29], v[6:7], v[14:15] op_sel_hi:[1,0,1]
	v_pk_fma_f32 v[16:17], v[26:27], v[6:7], v[16:17] op_sel_hi:[1,0,1]
	v_pk_fma_f32 v[18:19], v[28:29], v[6:7], v[18:19] op_sel:[0,1,0]
	v_pk_fma_f32 v[20:21], v[26:27], v[6:7], v[20:21] op_sel:[0,1,0]
	v_pk_fma_f32 v[22:23], v[28:29], v[8:9], v[22:23] op_sel_hi:[1,0,1]
	v_pk_fma_f32 v[24:25], v[26:27], v[8:9], v[24:25] op_sel_hi:[1,0,1]
	v_pk_fma_f32 v[6:7], v[28:29], v[78:79], v[38:39] op_sel_hi:[1,0,1]
	v_pk_fma_f32 v[8:9], v[26:27], v[78:79], v[44:45] op_sel_hi:[1,0,1]
	v_pk_fma_f32 v[10:11], v[28:29], v[80:81], v[74:75] op_sel_hi:[1,0,1]
	v_pk_fma_f32 v[12:13], v[26:27], v[80:81], v[72:73] op_sel_hi:[1,0,1]
	v_pk_fma_f32 v[40:41], v[28:29], v[82:83], v[40:41] op_sel_hi:[1,0,1]
	v_pk_fma_f32 v[42:43], v[26:27], v[82:83], v[42:43] op_sel_hi:[1,0,1]
	ds_read_b128 v[26:29], v77 offset:256
	v_add_co_u32_e32 v38, vcc, s14, v56
	s_waitcnt lgkmcnt(1)
	v_mov_b32_e32 v44, v33
	v_addc_co_u32_e32 v39, vcc, -1, v57, vcc
	v_pk_fma_f32 v[46:47], v[4:5], v[30:31], v[46:47] op_sel_hi:[1,0,1]
	v_pk_fma_f32 v[48:49], v[2:3], v[30:31], v[48:49] op_sel_hi:[1,0,1]
	v_pk_fma_f32 v[50:51], v[4:5], v[30:31], v[50:51] op_sel:[0,1,0]
	v_pk_fma_f32 v[58:59], v[2:3], v[30:31], v[58:59] op_sel:[0,1,0]
	v_pk_fma_f32 v[60:61], v[4:5], v[32:33], v[60:61] op_sel_hi:[1,0,1]
	v_pk_fma_f32 v[62:63], v[2:3], v[32:33], v[62:63] op_sel_hi:[1,0,1]
	ds_read_b128 v[30:33], v77 offset:272
	s_waitcnt lgkmcnt(1)
	v_pk_fma_f32 v[64:65], v[4:5], v[26:27], v[64:65] op_sel_hi:[1,0,1]
	v_pk_fma_f32 v[66:67], v[2:3], v[26:27], v[66:67] op_sel_hi:[1,0,1]
	v_pk_fma_f32 v[34:35], v[4:5], v[26:27], v[34:35] op_sel:[0,1,0]
	v_pk_fma_f32 v[36:37], v[2:3], v[26:27], v[36:37] op_sel:[0,1,0]
	v_pk_fma_f32 v[68:69], v[4:5], v[28:29], v[68:69] op_sel_hi:[1,0,1]
	v_pk_fma_f32 v[70:71], v[2:3], v[28:29], v[70:71] op_sel_hi:[1,0,1]
	v_mov_b32_e32 v72, v29
	s_waitcnt vmcnt(15)
	v_mov_b64_e32 v[26:27], v[154:155]
	v_mov_b64_e32 v[28:29], v[156:157]
	v_add_co_u32_e32 v194, vcc, 0x54000, v56
	s_nop 1
	v_addc_co_u32_e32 v195, vcc, 0, v57, vcc
	global_load_dwordx4 v[154:157], v[194:195], off nt
	s_mov_b32 s14, 0xfffa0000
	v_add_co_u32_e32 v74, vcc, s14, v56
	v_pk_fma_f32 v[38:39], v[4:5], v[44:45], v[6:7] op_sel_hi:[1,0,1]
	s_nop 0
	v_addc_co_u32_e32 v75, vcc, -1, v57, vcc
	v_pk_fma_f32 v[44:45], v[2:3], v[44:45], v[8:9] op_sel_hi:[1,0,1]
	s_waitcnt vmcnt(15)
	v_mov_b64_e32 v[6:7], v[158:159]
	v_mov_b64_e32 v[8:9], v[160:161]
	v_add_co_u32_e32 v194, vcc, 0x60000, v56
	s_nop 1
	v_addc_co_u32_e32 v195, vcc, 0, v57, vcc
	global_load_dwordx4 v[158:161], v[194:195], off nt
	s_waitcnt lgkmcnt(0)
	v_pk_fma_f32 v[14:15], v[4:5], v[30:31], v[14:15] op_sel_hi:[1,0,1]
	v_pk_fma_f32 v[16:17], v[2:3], v[30:31], v[16:17] op_sel_hi:[1,0,1]
	v_pk_fma_f32 v[18:19], v[4:5], v[30:31], v[18:19] op_sel:[0,1,0]
	v_pk_fma_f32 v[20:21], v[2:3], v[30:31], v[20:21] op_sel:[0,1,0]
	v_mov_b32_e32 v30, v33
	v_pk_fma_f32 v[22:23], v[4:5], v[32:33], v[22:23] op_sel_hi:[1,0,1]
	v_pk_fma_f32 v[24:25], v[2:3], v[32:33], v[24:25] op_sel_hi:[1,0,1]
	v_pk_fma_f32 v[74:75], v[4:5], v[72:73], v[10:11] op_sel_hi:[1,0,1]
	v_pk_fma_f32 v[72:73], v[2:3], v[72:73], v[12:13] op_sel_hi:[1,0,1]
	v_pk_fma_f32 v[40:41], v[4:5], v[30:31], v[40:41] op_sel_hi:[1,0,1]
	v_pk_fma_f32 v[42:43], v[2:3], v[30:31], v[42:43] op_sel_hi:[1,0,1]
	ds_read_b128 v[2:5], v77 offset:288
	ds_read_b128 v[10:13], v77 offset:304
	s_mov_b32 s14, 0xfffac000
	s_waitcnt lgkmcnt(1)
	v_mov_b32_e32 v78, v5
	s_waitcnt lgkmcnt(0)
	v_mov_b32_e32 v80, v13
	v_pk_fma_f32 v[46:47], v[28:29], v[2:3], v[46:47] op_sel_hi:[1,0,1]
	v_pk_fma_f32 v[48:49], v[26:27], v[2:3], v[48:49] op_sel_hi:[1,0,1]
	v_pk_fma_f32 v[50:51], v[28:29], v[2:3], v[50:51] op_sel:[0,1,0]
	v_pk_fma_f32 v[58:59], v[26:27], v[2:3], v[58:59] op_sel:[0,1,0]
	v_pk_fma_f32 v[60:61], v[28:29], v[4:5], v[60:61] op_sel_hi:[1,0,1]
	v_pk_fma_f32 v[62:63], v[26:27], v[4:5], v[62:63] op_sel_hi:[1,0,1]
	ds_read_b128 v[2:5], v77 offset:320
	ds_read_b128 v[30:33], v77 offset:336
	v_pk_fma_f32 v[64:65], v[28:29], v[10:11], v[64:65] op_sel_hi:[1,0,1]
	v_pk_fma_f32 v[66:67], v[26:27], v[10:11], v[66:67] op_sel_hi:[1,0,1]
	v_pk_fma_f32 v[34:35], v[28:29], v[10:11], v[34:35] op_sel:[0,1,0]
	s_waitcnt lgkmcnt(1)
	v_mov_b32_e32 v82, v5
	v_pk_fma_f32 v[36:37], v[26:27], v[10:11], v[36:37] op_sel:[0,1,0]
	v_pk_fma_f32 v[68:69], v[28:29], v[12:13], v[68:69] op_sel_hi:[1,0,1]
	v_pk_fma_f32 v[70:71], v[26:27], v[12:13], v[70:71] op_sel_hi:[1,0,1]
	v_pk_fma_f32 v[14:15], v[28:29], v[2:3], v[14:15] op_sel_hi:[1,0,1]
	v_pk_fma_f32 v[16:17], v[26:27], v[2:3], v[16:17] op_sel_hi:[1,0,1]
	v_pk_fma_f32 v[18:19], v[28:29], v[2:3], v[18:19] op_sel:[0,1,0]
	v_pk_fma_f32 v[20:21], v[26:27], v[2:3], v[20:21] op_sel:[0,1,0]
	v_pk_fma_f32 v[22:23], v[28:29], v[4:5], v[22:23] op_sel_hi:[1,0,1]
	v_pk_fma_f32 v[24:25], v[26:27], v[4:5], v[24:25] op_sel_hi:[1,0,1]
	v_pk_fma_f32 v[2:3], v[28:29], v[78:79], v[38:39] op_sel_hi:[1,0,1]
	v_pk_fma_f32 v[4:5], v[26:27], v[78:79], v[44:45] op_sel_hi:[1,0,1]
	v_pk_fma_f32 v[10:11], v[28:29], v[80:81], v[74:75] op_sel_hi:[1,0,1]
	v_pk_fma_f32 v[12:13], v[26:27], v[80:81], v[72:73] op_sel_hi:[1,0,1]
	v_pk_fma_f32 v[40:41], v[28:29], v[82:83], v[40:41] op_sel_hi:[1,0,1]
	v_pk_fma_f32 v[42:43], v[26:27], v[82:83], v[42:43] op_sel_hi:[1,0,1]
	ds_read_b128 v[26:29], v77 offset:352
	v_add_co_u32_e32 v38, vcc, s14, v56
	s_waitcnt lgkmcnt(1)
	v_mov_b32_e32 v44, v33
	v_addc_co_u32_e32 v39, vcc, -1, v57, vcc
	v_pk_fma_f32 v[46:47], v[8:9], v[30:31], v[46:47] op_sel_hi:[1,0,1]
	v_pk_fma_f32 v[48:49], v[6:7], v[30:31], v[48:49] op_sel_hi:[1,0,1]
	v_pk_fma_f32 v[50:51], v[8:9], v[30:31], v[50:51] op_sel:[0,1,0]
	v_pk_fma_f32 v[58:59], v[6:7], v[30:31], v[58:59] op_sel:[0,1,0]
	v_pk_fma_f32 v[60:61], v[8:9], v[32:33], v[60:61] op_sel_hi:[1,0,1]
	v_pk_fma_f32 v[62:63], v[6:7], v[32:33], v[62:63] op_sel_hi:[1,0,1]
	ds_read_b128 v[30:33], v77 offset:368
	s_waitcnt lgkmcnt(1)
	v_pk_fma_f32 v[64:65], v[8:9], v[26:27], v[64:65] op_sel_hi:[1,0,1]
	v_pk_fma_f32 v[66:67], v[6:7], v[26:27], v[66:67] op_sel_hi:[1,0,1]
	v_pk_fma_f32 v[34:35], v[8:9], v[26:27], v[34:35] op_sel:[0,1,0]
	v_pk_fma_f32 v[36:37], v[6:7], v[26:27], v[36:37] op_sel:[0,1,0]
	v_pk_fma_f32 v[68:69], v[8:9], v[28:29], v[68:69] op_sel_hi:[1,0,1]
	v_pk_fma_f32 v[70:71], v[6:7], v[28:29], v[70:71] op_sel_hi:[1,0,1]
	v_mov_b32_e32 v72, v29
	s_waitcnt vmcnt(15)
	v_mov_b64_e32 v[26:27], v[162:163]
	v_mov_b64_e32 v[28:29], v[164:165]
	v_add_co_u32_e32 v194, vcc, 0x6c000, v56
	s_nop 1
	v_addc_co_u32_e32 v195, vcc, 0, v57, vcc
	global_load_dwordx4 v[162:165], v[194:195], off nt
	s_mov_b32 s14, 0xfffb8000
	v_add_co_u32_e32 v74, vcc, s14, v56
	v_pk_fma_f32 v[38:39], v[8:9], v[44:45], v[2:3] op_sel_hi:[1,0,1]
	s_nop 0
	v_addc_co_u32_e32 v75, vcc, -1, v57, vcc
	v_pk_fma_f32 v[44:45], v[6:7], v[44:45], v[4:5] op_sel_hi:[1,0,1]
	s_waitcnt vmcnt(15)
	v_mov_b64_e32 v[2:3], v[166:167]
	v_mov_b64_e32 v[4:5], v[168:169]
	v_add_co_u32_e32 v194, vcc, 0x78000, v56
	s_nop 1
	v_addc_co_u32_e32 v195, vcc, 0, v57, vcc
	global_load_dwordx4 v[166:169], v[194:195], off nt
	s_waitcnt lgkmcnt(0)
	v_pk_fma_f32 v[14:15], v[8:9], v[30:31], v[14:15] op_sel_hi:[1,0,1]
	v_pk_fma_f32 v[16:17], v[6:7], v[30:31], v[16:17] op_sel_hi:[1,0,1]
	v_pk_fma_f32 v[18:19], v[8:9], v[30:31], v[18:19] op_sel:[0,1,0]
	v_pk_fma_f32 v[20:21], v[6:7], v[30:31], v[20:21] op_sel:[0,1,0]
	v_mov_b32_e32 v30, v33
	v_pk_fma_f32 v[22:23], v[8:9], v[32:33], v[22:23] op_sel_hi:[1,0,1]
	v_pk_fma_f32 v[24:25], v[6:7], v[32:33], v[24:25] op_sel_hi:[1,0,1]
	v_pk_fma_f32 v[74:75], v[8:9], v[72:73], v[10:11] op_sel_hi:[1,0,1]
	v_pk_fma_f32 v[72:73], v[6:7], v[72:73], v[12:13] op_sel_hi:[1,0,1]
	v_pk_fma_f32 v[40:41], v[8:9], v[30:31], v[40:41] op_sel_hi:[1,0,1]
	v_pk_fma_f32 v[42:43], v[6:7], v[30:31], v[42:43] op_sel_hi:[1,0,1]
	ds_read_b128 v[6:9], v77 offset:384
	ds_read_b128 v[10:13], v77 offset:400
	s_mov_b32 s14, 0xfffc4000
	s_waitcnt lgkmcnt(1)
	v_mov_b32_e32 v78, v9
	s_waitcnt lgkmcnt(0)
	v_mov_b32_e32 v80, v13
	v_pk_fma_f32 v[46:47], v[28:29], v[6:7], v[46:47] op_sel_hi:[1,0,1]
	v_pk_fma_f32 v[48:49], v[26:27], v[6:7], v[48:49] op_sel_hi:[1,0,1]
	v_pk_fma_f32 v[50:51], v[28:29], v[6:7], v[50:51] op_sel:[0,1,0]
	v_pk_fma_f32 v[58:59], v[26:27], v[6:7], v[58:59] op_sel:[0,1,0]
	v_pk_fma_f32 v[60:61], v[28:29], v[8:9], v[60:61] op_sel_hi:[1,0,1]
	v_pk_fma_f32 v[62:63], v[26:27], v[8:9], v[62:63] op_sel_hi:[1,0,1]
	ds_read_b128 v[6:9], v77 offset:416
	ds_read_b128 v[30:33], v77 offset:432
	v_pk_fma_f32 v[64:65], v[28:29], v[10:11], v[64:65] op_sel_hi:[1,0,1]
	v_pk_fma_f32 v[66:67], v[26:27], v[10:11], v[66:67] op_sel_hi:[1,0,1]
	v_pk_fma_f32 v[34:35], v[28:29], v[10:11], v[34:35] op_sel:[0,1,0]
	s_waitcnt lgkmcnt(1)
	v_mov_b32_e32 v82, v9
	v_pk_fma_f32 v[36:37], v[26:27], v[10:11], v[36:37] op_sel:[0,1,0]
	v_pk_fma_f32 v[68:69], v[28:29], v[12:13], v[68:69] op_sel_hi:[1,0,1]
	v_pk_fma_f32 v[70:71], v[26:27], v[12:13], v[70:71] op_sel_hi:[1,0,1]
	v_pk_fma_f32 v[14:15], v[28:29], v[6:7], v[14:15] op_sel_hi:[1,0,1]
	v_pk_fma_f32 v[16:17], v[26:27], v[6:7], v[16:17] op_sel_hi:[1,0,1]
	v_pk_fma_f32 v[18:19], v[28:29], v[6:7], v[18:19] op_sel:[0,1,0]
	v_pk_fma_f32 v[20:21], v[26:27], v[6:7], v[20:21] op_sel:[0,1,0]
	v_pk_fma_f32 v[22:23], v[28:29], v[8:9], v[22:23] op_sel_hi:[1,0,1]
	v_pk_fma_f32 v[24:25], v[26:27], v[8:9], v[24:25] op_sel_hi:[1,0,1]
	v_pk_fma_f32 v[6:7], v[28:29], v[78:79], v[38:39] op_sel_hi:[1,0,1]
	v_pk_fma_f32 v[8:9], v[26:27], v[78:79], v[44:45] op_sel_hi:[1,0,1]
	v_pk_fma_f32 v[10:11], v[28:29], v[80:81], v[74:75] op_sel_hi:[1,0,1]
	v_pk_fma_f32 v[12:13], v[26:27], v[80:81], v[72:73] op_sel_hi:[1,0,1]
	v_pk_fma_f32 v[40:41], v[28:29], v[82:83], v[40:41] op_sel_hi:[1,0,1]
	v_pk_fma_f32 v[42:43], v[26:27], v[82:83], v[42:43] op_sel_hi:[1,0,1]
	ds_read_b128 v[26:29], v77 offset:448
	v_add_co_u32_e32 v38, vcc, s14, v56
	s_waitcnt lgkmcnt(1)
	v_mov_b32_e32 v44, v33
	v_addc_co_u32_e32 v39, vcc, -1, v57, vcc
	v_pk_fma_f32 v[46:47], v[4:5], v[30:31], v[46:47] op_sel_hi:[1,0,1]
	v_pk_fma_f32 v[48:49], v[2:3], v[30:31], v[48:49] op_sel_hi:[1,0,1]
	v_pk_fma_f32 v[50:51], v[4:5], v[30:31], v[50:51] op_sel:[0,1,0]
	v_pk_fma_f32 v[58:59], v[2:3], v[30:31], v[58:59] op_sel:[0,1,0]
	v_pk_fma_f32 v[60:61], v[4:5], v[32:33], v[60:61] op_sel_hi:[1,0,1]
	v_pk_fma_f32 v[62:63], v[2:3], v[32:33], v[62:63] op_sel_hi:[1,0,1]
	ds_read_b128 v[30:33], v77 offset:464
	s_waitcnt lgkmcnt(1)
	v_pk_fma_f32 v[64:65], v[4:5], v[26:27], v[64:65] op_sel_hi:[1,0,1]
	v_pk_fma_f32 v[66:67], v[2:3], v[26:27], v[66:67] op_sel_hi:[1,0,1]
	v_pk_fma_f32 v[34:35], v[4:5], v[26:27], v[34:35] op_sel:[0,1,0]
	v_pk_fma_f32 v[36:37], v[2:3], v[26:27], v[36:37] op_sel:[0,1,0]
	v_pk_fma_f32 v[68:69], v[4:5], v[28:29], v[68:69] op_sel_hi:[1,0,1]
	v_pk_fma_f32 v[70:71], v[2:3], v[28:29], v[70:71] op_sel_hi:[1,0,1]
	v_mov_b32_e32 v72, v29
	s_waitcnt vmcnt(15)
	v_mov_b64_e32 v[26:27], v[170:171]
	v_mov_b64_e32 v[28:29], v[172:173]
	v_add_co_u32_e32 v194, vcc, 0x84000, v56
	s_nop 1
	v_addc_co_u32_e32 v195, vcc, 0, v57, vcc
	global_load_dwordx4 v[170:173], v[194:195], off nt
	s_mov_b32 s14, 0xfffd0000
	v_add_co_u32_e32 v74, vcc, s14, v56
	v_pk_fma_f32 v[38:39], v[4:5], v[44:45], v[6:7] op_sel_hi:[1,0,1]
	s_nop 0
	v_addc_co_u32_e32 v75, vcc, -1, v57, vcc
	v_pk_fma_f32 v[44:45], v[2:3], v[44:45], v[8:9] op_sel_hi:[1,0,1]
	s_waitcnt vmcnt(15)
	v_mov_b64_e32 v[6:7], v[174:175]
	v_mov_b64_e32 v[8:9], v[176:177]
	v_add_co_u32_e32 v194, vcc, 0x90000, v56
	s_nop 1
	v_addc_co_u32_e32 v195, vcc, 0, v57, vcc
	global_load_dwordx4 v[174:177], v[194:195], off nt
	s_waitcnt lgkmcnt(0)
	v_pk_fma_f32 v[14:15], v[4:5], v[30:31], v[14:15] op_sel_hi:[1,0,1]
	v_pk_fma_f32 v[16:17], v[2:3], v[30:31], v[16:17] op_sel_hi:[1,0,1]
	v_pk_fma_f32 v[18:19], v[4:5], v[30:31], v[18:19] op_sel:[0,1,0]
	v_pk_fma_f32 v[20:21], v[2:3], v[30:31], v[20:21] op_sel:[0,1,0]
	v_mov_b32_e32 v30, v33
	v_pk_fma_f32 v[22:23], v[4:5], v[32:33], v[22:23] op_sel_hi:[1,0,1]
	v_pk_fma_f32 v[24:25], v[2:3], v[32:33], v[24:25] op_sel_hi:[1,0,1]
	v_pk_fma_f32 v[74:75], v[4:5], v[72:73], v[10:11] op_sel_hi:[1,0,1]
	v_pk_fma_f32 v[72:73], v[2:3], v[72:73], v[12:13] op_sel_hi:[1,0,1]
	v_pk_fma_f32 v[40:41], v[4:5], v[30:31], v[40:41] op_sel_hi:[1,0,1]
	v_pk_fma_f32 v[42:43], v[2:3], v[30:31], v[42:43] op_sel_hi:[1,0,1]
	ds_read_b128 v[2:5], v77 offset:480
	ds_read_b128 v[10:13], v77 offset:496
	s_mov_b32 s14, 0xfffdc000
	s_waitcnt lgkmcnt(1)
	v_mov_b32_e32 v78, v5
	s_waitcnt lgkmcnt(0)
	v_mov_b32_e32 v80, v13
	v_pk_fma_f32 v[46:47], v[28:29], v[2:3], v[46:47] op_sel_hi:[1,0,1]
	v_pk_fma_f32 v[48:49], v[26:27], v[2:3], v[48:49] op_sel_hi:[1,0,1]
	v_pk_fma_f32 v[50:51], v[28:29], v[2:3], v[50:51] op_sel:[0,1,0]
	v_pk_fma_f32 v[58:59], v[26:27], v[2:3], v[58:59] op_sel:[0,1,0]
	v_pk_fma_f32 v[60:61], v[28:29], v[4:5], v[60:61] op_sel_hi:[1,0,1]
	v_pk_fma_f32 v[62:63], v[26:27], v[4:5], v[62:63] op_sel_hi:[1,0,1]
	ds_read_b128 v[2:5], v77 offset:512
	ds_read_b128 v[30:33], v77 offset:528
	v_pk_fma_f32 v[64:65], v[28:29], v[10:11], v[64:65] op_sel_hi:[1,0,1]
	v_pk_fma_f32 v[66:67], v[26:27], v[10:11], v[66:67] op_sel_hi:[1,0,1]
	v_pk_fma_f32 v[34:35], v[28:29], v[10:11], v[34:35] op_sel:[0,1,0]
	s_waitcnt lgkmcnt(1)
	v_mov_b32_e32 v82, v5
	v_pk_fma_f32 v[36:37], v[26:27], v[10:11], v[36:37] op_sel:[0,1,0]
	v_pk_fma_f32 v[68:69], v[28:29], v[12:13], v[68:69] op_sel_hi:[1,0,1]
	v_pk_fma_f32 v[70:71], v[26:27], v[12:13], v[70:71] op_sel_hi:[1,0,1]
	v_pk_fma_f32 v[14:15], v[28:29], v[2:3], v[14:15] op_sel_hi:[1,0,1]
	v_pk_fma_f32 v[16:17], v[26:27], v[2:3], v[16:17] op_sel_hi:[1,0,1]
	v_pk_fma_f32 v[18:19], v[28:29], v[2:3], v[18:19] op_sel:[0,1,0]
	v_pk_fma_f32 v[20:21], v[26:27], v[2:3], v[20:21] op_sel:[0,1,0]
	v_pk_fma_f32 v[22:23], v[28:29], v[4:5], v[22:23] op_sel_hi:[1,0,1]
	v_pk_fma_f32 v[24:25], v[26:27], v[4:5], v[24:25] op_sel_hi:[1,0,1]
	v_pk_fma_f32 v[10:11], v[28:29], v[78:79], v[38:39] op_sel_hi:[1,0,1]
	v_pk_fma_f32 v[12:13], v[26:27], v[78:79], v[44:45] op_sel_hi:[1,0,1]
	v_pk_fma_f32 v[2:3], v[28:29], v[80:81], v[74:75] op_sel_hi:[1,0,1]
	v_pk_fma_f32 v[4:5], v[26:27], v[80:81], v[72:73] op_sel_hi:[1,0,1]
	v_pk_fma_f32 v[40:41], v[28:29], v[82:83], v[40:41] op_sel_hi:[1,0,1]
	v_pk_fma_f32 v[42:43], v[26:27], v[82:83], v[42:43] op_sel_hi:[1,0,1]
	ds_read_b128 v[26:29], v77 offset:544
	s_waitcnt lgkmcnt(1)
	v_mov_b32_e32 v44, v33
	v_pk_fma_f32 v[46:47], v[8:9], v[30:31], v[46:47] op_sel_hi:[1,0,1]
	v_pk_fma_f32 v[48:49], v[6:7], v[30:31], v[48:49] op_sel_hi:[1,0,1]
	v_pk_fma_f32 v[50:51], v[8:9], v[30:31], v[50:51] op_sel:[0,1,0]
	v_pk_fma_f32 v[58:59], v[6:7], v[30:31], v[58:59] op_sel:[0,1,0]
	v_pk_fma_f32 v[60:61], v[8:9], v[32:33], v[60:61] op_sel_hi:[1,0,1]
	v_pk_fma_f32 v[62:63], v[6:7], v[32:33], v[62:63] op_sel_hi:[1,0,1]
	ds_read_b128 v[30:33], v77 offset:560
	v_add_co_u32_e32 v38, vcc, s14, v56
	s_mov_b32 s14, 0xfffe8000
	s_nop 0
	v_addc_co_u32_e32 v39, vcc, -1, v57, vcc
	s_waitcnt lgkmcnt(0)
	v_pk_fma_f32 v[72:73], v[8:9], v[30:31], v[14:15] op_sel_hi:[1,0,1]
	v_pk_fma_f32 v[74:75], v[6:7], v[30:31], v[16:17] op_sel_hi:[1,0,1]
	s_waitcnt vmcnt(15)
	v_mov_b64_e32 v[14:15], v[178:179]
	v_mov_b64_e32 v[16:17], v[180:181]
	v_add_co_u32_e32 v194, vcc, 0x9c000, v56
	s_nop 1
	v_addc_co_u32_e32 v195, vcc, 0, v57, vcc
	global_load_dwordx4 v[178:181], v[194:195], off nt
	v_pk_fma_f32 v[64:65], v[8:9], v[26:27], v[64:65] op_sel_hi:[1,0,1]
	v_pk_fma_f32 v[66:67], v[6:7], v[26:27], v[66:67] op_sel_hi:[1,0,1]
	v_pk_fma_f32 v[34:35], v[8:9], v[26:27], v[34:35] op_sel:[0,1,0]
	v_pk_fma_f32 v[26:27], v[6:7], v[26:27], v[36:37] op_sel:[0,1,0]
	v_pk_fma_f32 v[36:37], v[8:9], v[28:29], v[68:69] op_sel_hi:[1,0,1]
	v_pk_fma_f32 v[68:69], v[6:7], v[28:29], v[70:71] op_sel_hi:[1,0,1]
	v_add_co_u32_e32 v70, vcc, s14, v56
	v_pk_fma_f32 v[18:19], v[8:9], v[30:31], v[18:19] op_sel:[0,1,0]
	s_nop 0
	v_addc_co_u32_e32 v71, vcc, -1, v57, vcc
	v_pk_fma_f32 v[20:21], v[6:7], v[30:31], v[20:21] op_sel:[0,1,0]
	v_pk_fma_f32 v[22:23], v[8:9], v[32:33], v[22:23] op_sel_hi:[1,0,1]
	v_pk_fma_f32 v[24:25], v[6:7], v[32:33], v[24:25] op_sel_hi:[1,0,1]
	v_mov_b32_e32 v30, v33
	v_pk_fma_f32 v[32:33], v[8:9], v[44:45], v[10:11] op_sel_hi:[1,0,1]
	v_pk_fma_f32 v[38:39], v[6:7], v[44:45], v[12:13] op_sel_hi:[1,0,1]
	s_waitcnt vmcnt(15)
	v_mov_b64_e32 v[10:11], v[182:183]
	v_mov_b64_e32 v[12:13], v[184:185]
	v_add_co_u32_e32 v194, vcc, 0xa8000, v56
	s_nop 1
	v_addc_co_u32_e32 v195, vcc, 0, v57, vcc
	global_load_dwordx4 v[182:185], v[194:195], off nt
	v_mov_b32_e32 v28, v29
	v_pk_fma_f32 v[44:45], v[8:9], v[28:29], v[2:3] op_sel_hi:[1,0,1]
	v_pk_fma_f32 v[28:29], v[6:7], v[28:29], v[4:5] op_sel_hi:[1,0,1]
	v_pk_fma_f32 v[40:41], v[8:9], v[30:31], v[40:41] op_sel_hi:[1,0,1]
	v_pk_fma_f32 v[30:31], v[6:7], v[30:31], v[42:43] op_sel_hi:[1,0,1]
	ds_read_b128 v[2:5], v77 offset:576
	ds_read_b128 v[6:9], v77 offset:592
	s_mov_b32 s14, 0xffff4000
	s_waitcnt lgkmcnt(0)
	v_mov_b32_e32 v70, v9
	v_pk_fma_f32 v[42:43], v[16:17], v[2:3], v[46:47] op_sel_hi:[1,0,1]
	v_pk_fma_f32 v[46:47], v[14:15], v[2:3], v[48:49] op_sel_hi:[1,0,1]
	v_pk_fma_f32 v[48:49], v[16:17], v[2:3], v[50:51] op_sel:[0,1,0]
	v_pk_fma_f32 v[50:51], v[14:15], v[2:3], v[58:59] op_sel:[0,1,0]
	v_pk_fma_f32 v[58:59], v[16:17], v[4:5], v[60:61] op_sel_hi:[1,0,1]
	v_pk_fma_f32 v[60:61], v[14:15], v[4:5], v[62:63] op_sel_hi:[1,0,1]
	v_mov_b32_e32 v62, v5
	v_pk_fma_f32 v[64:65], v[16:17], v[6:7], v[64:65] op_sel_hi:[1,0,1]
	v_pk_fma_f32 v[66:67], v[14:15], v[6:7], v[66:67] op_sel_hi:[1,0,1]
	v_pk_fma_f32 v[34:35], v[16:17], v[6:7], v[34:35] op_sel:[0,1,0]
	v_pk_fma_f32 v[26:27], v[14:15], v[6:7], v[26:27] op_sel:[0,1,0]
	v_pk_fma_f32 v[36:37], v[16:17], v[8:9], v[36:37] op_sel_hi:[1,0,1]
	v_pk_fma_f32 v[68:69], v[14:15], v[8:9], v[68:69] op_sel_hi:[1,0,1]
	ds_read_b128 v[2:5], v77 offset:608
	ds_read_b128 v[6:9], v77 offset:624
	v_pk_fma_f32 v[32:33], v[16:17], v[62:63], v[32:33] op_sel_hi:[1,0,1]
	v_pk_fma_f32 v[38:39], v[14:15], v[62:63], v[38:39] op_sel_hi:[1,0,1]
	v_add_co_u32_e32 v62, vcc, s14, v56
	v_pk_fma_f32 v[44:45], v[16:17], v[70:71], v[44:45] op_sel_hi:[1,0,1]
	s_nop 0
	v_addc_co_u32_e32 v63, vcc, -1, v57, vcc
	v_pk_fma_f32 v[28:29], v[14:15], v[70:71], v[28:29] op_sel_hi:[1,0,1]
	s_waitcnt lgkmcnt(0)
	v_mov_b32_e32 v70, v9
	v_pk_fma_f32 v[42:43], v[12:13], v[6:7], v[42:43] op_sel_hi:[1,0,1]
	v_pk_fma_f32 v[46:47], v[10:11], v[6:7], v[46:47] op_sel_hi:[1,0,1]
	v_pk_fma_f32 v[48:49], v[12:13], v[6:7], v[48:49] op_sel:[0,1,0]
	v_pk_fma_f32 v[50:51], v[10:11], v[6:7], v[50:51] op_sel:[0,1,0]
	v_pk_fma_f32 v[58:59], v[12:13], v[8:9], v[58:59] op_sel_hi:[1,0,1]
	v_pk_fma_f32 v[78:79], v[10:11], v[8:9], v[60:61] op_sel_hi:[1,0,1]
	s_waitcnt vmcnt(15)
	v_mov_b64_e32 v[6:7], v[186:187]
	v_mov_b64_e32 v[8:9], v[188:189]
	v_add_co_u32_e32 v194, vcc, 0xb4000, v56
	s_nop 1
	v_addc_co_u32_e32 v195, vcc, 0, v57, vcc
	global_load_dwordx4 v[186:189], v[194:195], off nt
	v_pk_fma_f32 v[72:73], v[16:17], v[2:3], v[72:73] op_sel_hi:[1,0,1]
	v_pk_fma_f32 v[74:75], v[14:15], v[2:3], v[74:75] op_sel_hi:[1,0,1]
	v_pk_fma_f32 v[18:19], v[16:17], v[2:3], v[18:19] op_sel:[0,1,0]
	v_pk_fma_f32 v[20:21], v[14:15], v[2:3], v[20:21] op_sel:[0,1,0]
	v_mov_b32_e32 v2, v5
	v_pk_fma_f32 v[22:23], v[16:17], v[4:5], v[22:23] op_sel_hi:[1,0,1]
	v_pk_fma_f32 v[24:25], v[14:15], v[4:5], v[24:25] op_sel_hi:[1,0,1]
	v_pk_fma_f32 v[40:41], v[16:17], v[2:3], v[40:41] op_sel_hi:[1,0,1]
	v_pk_fma_f32 v[30:31], v[14:15], v[2:3], v[30:31] op_sel_hi:[1,0,1]
	ds_read_b128 v[2:5], v77 offset:640
	ds_read_b128 v[14:17], v77 offset:656
	v_pk_fma_f32 v[86:87], v[12:13], v[70:71], v[32:33] op_sel_hi:[1,0,1]
	v_pk_fma_f32 v[70:71], v[10:11], v[70:71], v[38:39] op_sel_hi:[1,0,1]
	s_mov_b64 s[14:15], 0xc0000
	s_waitcnt lgkmcnt(1)
	v_pk_fma_f32 v[80:81], v[12:13], v[2:3], v[64:65] op_sel_hi:[1,0,1]
	v_pk_fma_f32 v[66:67], v[10:11], v[2:3], v[66:67] op_sel_hi:[1,0,1]
	v_pk_fma_f32 v[34:35], v[12:13], v[2:3], v[34:35] op_sel:[0,1,0]
	v_pk_fma_f32 v[82:83], v[10:11], v[2:3], v[26:27] op_sel:[0,1,0]
	v_pk_fma_f32 v[84:85], v[12:13], v[4:5], v[36:37] op_sel_hi:[1,0,1]
	v_pk_fma_f32 v[68:69], v[10:11], v[4:5], v[68:69] op_sel_hi:[1,0,1]
	v_mov_b32_e32 v26, v5
	ds_read_b128 v[2:5], v77 offset:672
	s_waitcnt lgkmcnt(1)
	v_mov_b32_e32 v32, v17
	v_pk_fma_f32 v[92:93], v[12:13], v[14:15], v[18:19] op_sel:[0,1,0]
	v_pk_fma_f32 v[96:97], v[12:13], v[16:17], v[22:23] op_sel_hi:[1,0,1]
	v_pk_fma_f32 v[98:99], v[10:11], v[16:17], v[24:25] op_sel_hi:[1,0,1]
	ds_read_b128 v[16:19], v77 offset:688
	ds_read_b128 v[60:63], v77 offset:704
	v_pk_fma_f32 v[88:89], v[12:13], v[14:15], v[72:73] op_sel_hi:[1,0,1]
	v_pk_fma_f32 v[90:91], v[10:11], v[14:15], v[74:75] op_sel_hi:[1,0,1]
	v_pk_fma_f32 v[94:95], v[10:11], v[14:15], v[20:21] op_sel:[0,1,0]
	v_pk_fma_f32 v[20:21], v[12:13], v[26:27], v[44:45] op_sel_hi:[1,0,1]
	v_pk_fma_f32 v[22:23], v[10:11], v[26:27], v[28:29] op_sel_hi:[1,0,1]
	v_pk_fma_f32 v[24:25], v[12:13], v[32:33], v[40:41] op_sel_hi:[1,0,1]
	v_pk_fma_f32 v[26:27], v[10:11], v[32:33], v[30:31] op_sel_hi:[1,0,1]
	s_waitcnt lgkmcnt(1)
	v_mov_b32_e32 v64, v19
	v_pk_fma_f32 v[10:11], v[8:9], v[2:3], v[42:43] op_sel_hi:[1,0,1]
	v_pk_fma_f32 v[12:13], v[6:7], v[2:3], v[46:47] op_sel_hi:[1,0,1]
	v_pk_fma_f32 v[14:15], v[8:9], v[2:3], v[48:49] op_sel:[0,1,0]
	v_pk_fma_f32 v[30:31], v[6:7], v[2:3], v[50:51] op_sel:[0,1,0]
	v_mov_b32_e32 v2, v5
	v_pk_fma_f32 v[72:73], v[8:9], v[4:5], v[58:59] op_sel_hi:[1,0,1]
	v_pk_fma_f32 v[74:75], v[6:7], v[4:5], v[78:79] op_sel_hi:[1,0,1]
	v_pk_fma_f32 v[38:39], v[8:9], v[16:17], v[34:35] op_sel:[0,1,0]
	v_pk_fma_f32 v[28:29], v[8:9], v[2:3], v[86:87] op_sel_hi:[1,0,1]
	v_pk_fma_f32 v[34:35], v[6:7], v[2:3], v[70:71] op_sel_hi:[1,0,1]
	s_waitcnt vmcnt(15)
	v_mov_b64_e32 v[2:3], v[190:191]
	v_mov_b64_e32 v[4:5], v[192:193]
	v_add_co_u32_e32 v194, vcc, 0xc0000, v56
	s_nop 1
	v_addc_co_u32_e32 v195, vcc, 0, v57, vcc
	global_load_dwordx4 v[190:193], v[194:195], off nt
	v_pk_fma_f32 v[36:37], v[6:7], v[16:17], v[66:67] op_sel_hi:[1,0,1]
	s_waitcnt lgkmcnt(0)
	v_mov_b32_e32 v66, v63
	v_pk_fma_f32 v[32:33], v[8:9], v[16:17], v[80:81] op_sel_hi:[1,0,1]
	v_pk_fma_f32 v[40:41], v[6:7], v[16:17], v[82:83] op_sel:[0,1,0]
	v_pk_fma_f32 v[42:43], v[8:9], v[18:19], v[84:85] op_sel_hi:[1,0,1]
	v_pk_fma_f32 v[44:45], v[6:7], v[18:19], v[68:69] op_sel_hi:[1,0,1]
	ds_read_b128 v[16:19], v77 offset:720
	v_pk_fma_f32 v[68:69], v[8:9], v[64:65], v[20:21] op_sel_hi:[1,0,1]
	v_pk_fma_f32 v[70:71], v[6:7], v[64:65], v[22:23] op_sel_hi:[1,0,1]
	v_pk_fma_f32 v[64:65], v[8:9], v[66:67], v[24:25] op_sel_hi:[1,0,1]
	v_pk_fma_f32 v[66:67], v[6:7], v[66:67], v[26:27] op_sel_hi:[1,0,1]
	ds_read_b128 v[20:23], v77 offset:736
	ds_read_b128 v[24:27], v77 offset:752
	v_pk_fma_f32 v[46:47], v[8:9], v[60:61], v[88:89] op_sel_hi:[1,0,1]
	v_pk_fma_f32 v[48:49], v[6:7], v[60:61], v[90:91] op_sel_hi:[1,0,1]
	v_pk_fma_f32 v[50:51], v[8:9], v[60:61], v[92:93] op_sel:[0,1,0]
	v_pk_fma_f32 v[58:59], v[6:7], v[60:61], v[94:95] op_sel:[0,1,0]
	v_pk_fma_f32 v[60:61], v[8:9], v[62:63], v[96:97] op_sel_hi:[1,0,1]
	v_pk_fma_f32 v[62:63], v[6:7], v[62:63], v[98:99] op_sel_hi:[1,0,1]
	v_lshl_add_u64 v[56:57], v[56:57], 0, s[14:15]
	s_waitcnt lgkmcnt(2)
	v_pk_fma_f32 v[8:9], v[4:5], v[16:17], v[10:11] op_sel_hi:[1,0,1]
	v_pk_fma_f32 v[6:7], v[2:3], v[16:17], v[12:13] op_sel_hi:[1,0,1]
	v_pk_fma_f32 v[12:13], v[4:5], v[16:17], v[14:15] op_sel:[0,1,0]
	v_pk_fma_f32 v[10:11], v[2:3], v[16:17], v[30:31] op_sel:[0,1,0]
	v_pk_fma_f32 v[16:17], v[4:5], v[18:19], v[72:73] op_sel_hi:[1,0,1]
	v_pk_fma_f32 v[14:15], v[2:3], v[18:19], v[74:75] op_sel_hi:[1,0,1]
	v_mov_b32_e32 v18, v19
	s_waitcnt lgkmcnt(1)
	v_mov_b32_e32 v72, v23
	s_waitcnt lgkmcnt(0)
	v_mov_b32_e32 v74, v27
	v_pk_fma_f32 v[30:31], v[4:5], v[18:19], v[28:29] op_sel_hi:[1,0,1]
	v_pk_fma_f32 v[28:29], v[2:3], v[18:19], v[34:35] op_sel_hi:[1,0,1]
	v_pk_fma_f32 v[34:35], v[4:5], v[20:21], v[32:33] op_sel_hi:[1,0,1]
	v_pk_fma_f32 v[32:33], v[2:3], v[20:21], v[36:37] op_sel_hi:[1,0,1]
	v_pk_fma_f32 v[38:39], v[4:5], v[20:21], v[38:39] op_sel:[0,1,0]
	v_pk_fma_f32 v[36:37], v[2:3], v[20:21], v[40:41] op_sel:[0,1,0]
	v_pk_fma_f32 v[20:21], v[4:5], v[22:23], v[42:43] op_sel_hi:[1,0,1]
	v_pk_fma_f32 v[18:19], v[2:3], v[22:23], v[44:45] op_sel_hi:[1,0,1]
	v_pk_fma_f32 v[42:43], v[4:5], v[72:73], v[68:69] op_sel_hi:[1,0,1]
	v_pk_fma_f32 v[40:41], v[2:3], v[72:73], v[70:71] op_sel_hi:[1,0,1]
	v_pk_fma_f32 v[46:47], v[4:5], v[24:25], v[46:47] op_sel_hi:[1,0,1]
	v_pk_fma_f32 v[44:45], v[2:3], v[24:25], v[48:49] op_sel_hi:[1,0,1]
	v_pk_fma_f32 v[50:51], v[4:5], v[24:25], v[50:51] op_sel:[0,1,0]
	v_pk_fma_f32 v[48:49], v[2:3], v[24:25], v[58:59] op_sel:[0,1,0]
	v_pk_fma_f32 v[24:25], v[4:5], v[26:27], v[60:61] op_sel_hi:[1,0,1]
	v_pk_fma_f32 v[22:23], v[2:3], v[26:27], v[62:63] op_sel_hi:[1,0,1]
	v_pk_fma_f32 v[4:5], v[4:5], v[74:75], v[64:65] op_sel_hi:[1,0,1]
	v_pk_fma_f32 v[2:3], v[2:3], v[74:75], v[66:67] op_sel_hi:[1,0,1]
	s_cbranch_scc0 .LBB0_34
	s_barrier
	ds_write_b128 v76, v[6:9]
	ds_write_b128 v76, v[10:13] offset:1024
	ds_write_b128 v76, v[14:17] offset:2048
	ds_write_b128 v76, v[28:31] offset:3072
	ds_write_b128 v76, v[32:35] offset:4096
	ds_write_b128 v76, v[36:39] offset:5120
	ds_write_b128 v76, v[18:21] offset:6144
	ds_write_b128 v76, v[40:43] offset:7168
	ds_write_b128 v76, v[44:47] offset:8192
	ds_write_b128 v76, v[48:51] offset:9216
	ds_write_b128 v76, v[22:25] offset:10240
	ds_write_b128 v76, v[2:5] offset:11264
	s_waitcnt lgkmcnt(0)
	s_barrier
	s_and_saveexec_b64 s[14:15], s[4:5]
	v_readlane_b32 s36, v250, 37
	v_readlane_b32 s40, v250, 41
	v_readlane_b32 s41, v250, 42
	v_readlane_b32 s37, v250, 38
	v_readlane_b32 s38, v250, 39
	v_readlane_b32 s39, v250, 40
	v_readlane_b32 s42, v250, 43
	v_readlane_b32 s43, v250, 44
	v_readlane_b32 s44, v250, 45
	v_readlane_b32 s45, v250, 46
	v_readlane_b32 s46, v250, 47
	v_readlane_b32 s47, v250, 48
	v_readlane_b32 s48, v250, 49
	v_readlane_b32 s49, v250, 50
	v_readlane_b32 s50, v250, 51
	v_readlane_b32 s51, v250, 52
	s_cbranch_execz .LBB0_23
	s_lshl_b64 s[16:17], s[12:13], 2
	s_add_u32 s16, s20, s16
	s_addc_u32 s17, s21, s17
	v_lshl_add_u32 v2, v1, 2, 0
	s_mov_b64 s[18:19], 0
	v_mov_b32_e32 v3, v1
